# weight-conversion f32 loads with sc1 nt instead of nt
# baseline (speedup 1.0000x reference)
; __device__ __forceinline__ void tconv_tile_w(const float* src, int N, int kb, int nb, bf16_t* dst, int ldd, float* tile, const float* kscale = nullptr) {
;     ...
; #pragma unroll
;     for (int p = 0; p < 8; ++p) { const int idx = tid + 512 * p, r = idx >> 6, c4 = idx & 63;
;         v[p] = __builtin_nontemporal_load((const f32x4*)(src + (size_t)(kb * 64 + r) * N + nb * 256 + c4 * 4)); }
.Ltc_advend_5:
	s_cmp_eq_u32 s43, 0
	s_cbranch_scc1 .Ltc_exit_1
	v_mad_u32_u24 v97, s49, 0, v96
	v_mad_u32_u24 v98, s49, 1, v96
	v_mad_u32_u24 v99, s49, 2, v96
	v_mad_u32_u24 v100, s49, 3, v96
	v_mad_u32_u24 v101, s49, 4, v96
	v_mad_u32_u24 v102, s49, 5, v96
	v_mad_u32_u24 v103, s49, 6, v96
	v_mad_u32_u24 v104, s49, 7, v96
	global_load_dwordx4 v[0:3], v97, s[44:45] sc1 nt
	global_load_dwordx4 v[4:7], v98, s[44:45] sc1 nt
	global_load_dwordx4 v[8:11], v99, s[44:45] sc1 nt
	global_load_dwordx4 v[12:15], v100, s[44:45] sc1 nt
	global_load_dwordx4 v[16:19], v101, s[44:45] sc1 nt
	global_load_dwordx4 v[20:23], v102, s[44:45] sc1 nt
	global_load_dwordx4 v[24:27], v103, s[44:45] sc1 nt
	global_load_dwordx4 v[28:31], v104, s[44:45] sc1 nt
	s_waitcnt lgkmcnt(0)
	s_mov_b64 s[50:51], s[46:47]
	s_mov_b32 s52, s48
	s_mov_b32 s59, s61
	s_mov_b64 s[68:69], s[76:77]
	s_mov_b64 s[70:71], s[78:79]
	s_mov_b64 s[72:73], s[80:81]
	s_mov_b64 s[74:75], s[82:83]

; __device__ __forceinline__ void tconv_tile_w(const float* src, int N, int kb, int nb, bf16_t* dst, int ldd, float* tile, const float* kscale = nullptr) {
;     ...
; #pragma unroll
;     for (int p = 0; p < 8; ++p) { const int idx = tid + 512 * p, r = idx >> 6, c4 = idx & 63;
;         v[p] = __builtin_nontemporal_load((const f32x4*)(src + (size_t)(kb * 64 + r) * N + nb * 256 + c4 * 4)); }
.Ltc_advend_41:
	s_cmp_eq_u32 s43, 0
	s_cbranch_scc1 .Ltc_skipA_73
	v_mad_u32_u24 v97, s49, 0, v96
	v_mad_u32_u24 v98, s49, 1, v96
	v_mad_u32_u24 v99, s49, 2, v96
	v_mad_u32_u24 v100, s49, 3, v96
	v_mad_u32_u24 v101, s49, 4, v96
	v_mad_u32_u24 v102, s49, 5, v96
	v_mad_u32_u24 v103, s49, 6, v96
	v_mad_u32_u24 v104, s49, 7, v96
	global_load_dwordx4 v[32:35], v97, s[44:45] sc1 nt
	global_load_dwordx4 v[36:39], v98, s[44:45] sc1 nt
	global_load_dwordx4 v[40:43], v99, s[44:45] sc1 nt
	global_load_dwordx4 v[44:47], v100, s[44:45] sc1 nt
	global_load_dwordx4 v[48:51], v101, s[44:45] sc1 nt
	global_load_dwordx4 v[52:55], v102, s[44:45] sc1 nt
	global_load_dwordx4 v[56:59], v103, s[44:45] sc1 nt
	global_load_dwordx4 v[60:63], v104, s[44:45] sc1 nt

; __device__ __forceinline__ void tconv_tile_w(const float* src, int N, int kb, int nb, bf16_t* dst, int ldd, float* tile, const float* kscale = nullptr) {
;     ...
; #pragma unroll
;     for (int p = 0; p < 8; ++p) { const int idx = tid + 512 * p, r = idx >> 6, c4 = idx & 63;
;         v[p] = __builtin_nontemporal_load((const f32x4*)(src + (size_t)(kb * 64 + r) * N + nb * 256 + c4 * 4)); }
.Ltc_advend_81:
	s_cmp_eq_u32 s43, 0
	s_cbranch_scc1 .Ltc_skipB_113
	v_mad_u32_u24 v97, s49, 0, v96
	v_mad_u32_u24 v98, s49, 1, v96
	v_mad_u32_u24 v99, s49, 2, v96
	v_mad_u32_u24 v100, s49, 3, v96
	v_mad_u32_u24 v101, s49, 4, v96
	v_mad_u32_u24 v102, s49, 5, v96
	v_mad_u32_u24 v103, s49, 6, v96
	v_mad_u32_u24 v104, s49, 7, v96
	global_load_dwordx4 v[0:3], v97, s[44:45] sc1 nt
	global_load_dwordx4 v[4:7], v98, s[44:45] sc1 nt
	global_load_dwordx4 v[8:11], v99, s[44:45] sc1 nt
	global_load_dwordx4 v[12:15], v100, s[44:45] sc1 nt
	global_load_dwordx4 v[16:19], v101, s[44:45] sc1 nt
	global_load_dwordx4 v[20:23], v102, s[44:45] sc1 nt
	global_load_dwordx4 v[24:27], v103, s[44:45] sc1 nt
	global_load_dwordx4 v[28:31], v104, s[44:45] sc1 nt
